# v26 plus LayerNorm/adaLN row loop: LN gain/bias loaded once, modulation vectors loaded with the row, no store drains
# speedup vs baseline: 1.0152x; 1.0016x over previous
; __device__ __forceinline__ void ln_pass(const float* src, float* dstx, const float* lg, const float* lb, const float* msc, const float* msh, bf16_t* Hout, float* statout, const LnRows R) {
;     const int lane = threadIdx.x & 63;
;     for (int row = R.rbase + R.gw; row < R.rend; row += R.ngw) {
;         const f32x4* xr = (const f32x4*)(src + (size_t)row * DM) + lane;
;         f32x4 v[4];
; #pragma unroll
;         for (int j = 0; j < 4; ++j) v[j] = xr[64 * j];
;         if (lg) {
;             float s = 0.f;
; #pragma unroll
;             for (int j = 0; j < 4; ++j) s += (v[j].x + v[j].y) + (v[j].z + v[j].w);
;             const float mean = wave_sum(s) * (1.f / DM); float s2 = 0.f;
; #pragma unroll
;             for (int j = 0; j < 4; ++j) { v[j] = v[j] - mean; s2 += (v[j].x * v[j].x + v[j].y * v[j].y) + (v[j].z * v[j].z + v[j].w * v[j].w); }
;             const float rstd = 1.f / sqrtf(wave_sum(s2) * (1.f / DM) + 1e-5f);
;             if (statout && lane == 0) { statout[2 * row] = mean; statout[2 * row + 1] = rstd; }
; #pragma unroll
;             for (int j = 0; j < 4; ++j) { const f32x4 g = *((const f32x4*)lg + lane + 64 * j), b = *((const f32x4*)lb + lane + 64 * j); v[j] = v[j] * rstd * g + b;
;                 if (dstx) *((f32x4*)(dstx + (size_t)row * DM) + lane + 64 * j) = v[j]; }
;         }
; template <int ph>
; __device__ __forceinline__ void run_phase(const Params& p, unsigned char* lds, const int vc, const LnRows lnl) {
;     ...
;                 else ln_pass(X, nullptr, p.in[I_LNG] + (0 * 2 + 1) * DM, p.in[I_LNB] + (0 * 2 + 1) * DM, modl + 1 * 1024, modl + 0 * 1024, Hb, (float*)(ws + WS_STAT) + 2 * T, lnl);
.LBB0_1530:
	s_cmp_lt_i32 s4, 13
	s_cselect_b64 s[0:1], -1, 0
	s_cmp_gt_i32 s5, 12
	s_cselect_b64 s[2:3], -1, 0
	s_and_b64 s[0:1], s[0:1], s[2:3]
	s_andn2_b64 vcc, exec, s[0:1]
	s_cbranch_vccnz .LBB0_1615
	v_add_u32_e32 v16, s90, v193
	v_cmp_gt_i32_e32 vcc, s66, v16
	s_and_saveexec_b64 s[4:5], vcc
	s_cbranch_execz .LBB0_1536
	v_and_b32_e32 v4, 63, v192
	v_readlane_b32 s16, v246, 0
	v_lshlrev_b32_e32 v0, 4, v4
	v_mov_b32_e32 v1, 0
	v_readlane_b32 s22, v246, 6
	v_readlane_b32 s23, v246, 7
	s_mov_b64 s[0:1], 0x1000
	v_ashrrev_i32_e32 v17, 31, v16
	v_lshl_add_u64 v[2:3], s[22:23], 0, v[0:1]
	v_lshl_add_u64 v[18:19], v[2:3], 0, s[0:1]
	v_lshl_add_u64 v[2:3], s[92:93], 0, v[0:1]
	v_lshl_add_u64 v[20:21], v[2:3], 0, s[0:1]
	v_lshl_add_u64 v[2:3], s[96:97], 0, v[0:1]
	s_mov_b64 s[0:1], 0x19000
	v_lshl_add_u64 v[22:23], v[2:3], 0, s[0:1]
	s_mov_b64 s[0:1], 0x18000
	v_lshl_add_u64 v[24:25], v[2:3], 0, s[0:1]
	v_lshlrev_b64 v[2:3], 11, v[16:17]
	v_lshl_or_b32 v2, v4, 3, v2
	v_lshl_add_u64 v[2:3], s[96:97], 0, v[2:3]
	s_mov_b64 s[0:1], 0x4c00000
	v_lshl_add_u64 v[28:29], v[2:3], 0, s[0:1]
	v_lshlrev_b64 v[2:3], 12, v[16:17]
	s_add_u32 s14, s96, 0x640000
	v_or_b32_e32 v2, v2, v0
	s_addc_u32 s15, s97, 0
	v_readlane_b32 s17, v246, 1
	v_readlane_b32 s18, v246, 2
	v_readlane_b32 s19, v246, 3
	v_readlane_b32 s20, v246, 4
	v_readlane_b32 s21, v246, 5
	s_ashr_i32 s9, s8, 31
	v_lshl_add_u64 v[0:1], s[94:95], 0, v[2:3]
	s_mov_b64 s[0:1], 0xc00
	v_cmp_eq_u32_e64 s[2:3], 0, v4
	v_lshlrev_b32_e32 v26, 1, v16
	s_lshl_b32 s6, s8, 1
	s_lshl_b64 s[16:17], s[8:9], 11
	v_lshl_add_u64 v[30:31], v[0:1], 0, s[0:1]
	s_lshl_b64 s[18:19], s[8:9], 12
	s_mov_b64 s[20:21], 0
	v_mov_b32_e32 v17, 0x3727c5ac
	s_mov_b32 s7, 0xf800000
	v_mov_b32_e32 v33, 0x260
	s_movk_i32 s9, 0x7fff
	s_mov_b32 s13, 0xffff0000
	global_load_dwordx4 v[96:99], v[20:21], off
	global_load_dwordx4 v[100:103], v[18:19], off
	global_load_dwordx4 v[104:107], v[18:19], off offset:1024
	global_load_dwordx4 v[108:111], v[20:21], off offset:1024
	global_load_dwordx4 v[112:115], v[20:21], off offset:2048
	global_load_dwordx4 v[116:119], v[18:19], off offset:2048
	global_load_dwordx4 v[120:123], v[18:19], off offset:3072
	global_load_dwordx4 v[124:127], v[20:21], off offset:3072
	s_branch .LBB0_1534
.LBB0_1533:
	s_or_b64 exec, exec, s[0:1]
	v_mov_b64_e32 v[34:35], v[96:97]
	v_mov_b64_e32 v[36:37], v[98:99]
	v_mov_b64_e32 v[38:39], v[100:101]
	v_mov_b64_e32 v[40:41], v[102:103]
	v_mov_b64_e32 v[42:43], v[104:105]
	v_mov_b64_e32 v[44:45], v[106:107]
	v_mov_b64_e32 v[46:47], v[108:109]
	v_mov_b64_e32 v[48:49], v[110:111]
	v_mov_b64_e32 v[50:51], v[112:113]
	v_mov_b64_e32 v[52:53], v[114:115]
	v_mov_b64_e32 v[54:55], v[116:117]
	v_mov_b64_e32 v[56:57], v[118:119]
	v_mov_b64_e32 v[58:59], v[120:121]
	v_mov_b64_e32 v[60:61], v[122:123]
	v_mov_b64_e32 v[62:63], v[124:125]
	v_mov_b64_e32 v[64:65], v[126:127]
	v_pk_mul_f32 v[74:75], v[0:1], v[32:33] op_sel_hi:[1,0]
	v_ashrrev_i32_e32 v0, 31, v16
	v_lshrrev_b32_e32 v0, 19, v0
	v_add_u32_e32 v0, v16, v0
	v_ashrrev_i32_e32 v0, 13, v0
	v_mul_i32_i24_e32 v0, 0x1800, v0
	v_ashrrev_i32_e32 v1, 31, v0
	v_lshlrev_b64 v[0:1], 2, v[0:1]
	v_lshl_add_u64 v[76:77], v[22:23], 0, v[0:1]
	v_pk_mul_f32 v[14:15], v[14:15], v[32:33] op_sel_hi:[1,0]
	v_pk_mul_f32 v[12:13], v[12:13], v[32:33] op_sel_hi:[1,0]
	v_pk_mul_f32 v[66:67], v[10:11], v[32:33] op_sel_hi:[1,0]
	v_pk_mul_f32 v[68:69], v[8:9], v[32:33] op_sel_hi:[1,0]
	v_pk_mul_f32 v[70:71], v[6:7], v[32:33] op_sel_hi:[1,0]
	v_pk_mul_f32 v[72:73], v[4:5], v[32:33] op_sel_hi:[1,0]
	v_lshl_add_u64 v[78:79], v[24:25], 0, v[0:1]
	v_pk_mul_f32 v[2:3], v[2:3], v[32:33] op_sel_hi:[1,0]
	v_add_u32_e32 v16, s8, v16
	v_add_u32_e32 v26, s6, v26
	v_lshl_add_u64 v[30:31], v[30:31], 0, s[18:19]
	v_pk_fma_f32 v[14:15], v[14:15], v[40:41], v[36:37]
	v_pk_fma_f32 v[12:13], v[12:13], v[38:39], v[34:35]
	v_pk_fma_f32 v[34:35], v[66:67], v[44:45], v[48:49]
	v_pk_fma_f32 v[36:37], v[68:69], v[42:43], v[46:47]
	v_pk_mov_b32 v[42:43], v[12:13], v[14:15] op_sel:[1,0]
	v_mov_b32_e32 v44, v12
	v_mov_b32_e32 v45, v15
	v_pk_mov_b32 v[46:47], v[36:37], v[34:35] op_sel:[1,0]
	v_mov_b32_e32 v48, v36
	v_mov_b32_e32 v49, v35
	v_pk_add_f32 v[42:43], v[42:43], v[44:45]
	v_pk_add_f32 v[44:45], v[46:47], v[48:49]
	v_pk_fma_f32 v[38:39], v[70:71], v[56:57], v[52:53]
	v_pk_fma_f32 v[40:41], v[72:73], v[54:55], v[50:51]
	v_pk_fma_f32 v[0:1], v[2:3], v[60:61], v[64:65]
	v_pk_fma_f32 v[2:3], v[74:75], v[58:59], v[62:63]
	v_add_f32_e32 v27, v42, v43
	v_pk_add_f32 v[42:43], v[44:45], v[44:45] op_sel:[0,1] op_sel_hi:[1,0]
	v_add_f32_e32 v50, v40, v41
	v_add_f32_e32 v52, v38, v39
	v_mov_b32_e32 v55, v2
	v_mov_b32_e32 v51, v0
	v_mov_b32_e32 v53, v1
	v_add_f32_e32 v54, 0, v27
	v_mov_b32_e32 v43, v3
	v_pk_add_f32 v[46:47], v[50:51], v[52:53]
	v_pk_add_f32 v[42:43], v[54:55], v[42:43]
	s_waitcnt vmcnt(0)
; __device__ __forceinline__ unsigned pk2(float lo, float hi) { return f2bf(lo) | (f2bf(hi) << 16); }
; __device__ __forceinline__ void ln_pass(const float* src, float* dstx, const float* lg, const float* lb, const float* msc, const float* msh, bf16_t* Hout, float* statout, const LnRows R) {
;     ...
;         if (Hout) {
;             float s = 0.f;
; #pragma unroll
;             for (int j = 0; j < 4; ++j) s += (v[j].x + v[j].y) + (v[j].z + v[j].w);
;             const float mean = wave_sum(s) * (1.f / DM); float s2 = 0.f;
; #pragma unroll
;             for (int j = 0; j < 4; ++j) { v[j] = v[j] - mean; s2 += (v[j].x * v[j].x + v[j].y * v[j].y) + (v[j].z * v[j].z + v[j].w * v[j].w); }
;             const float rstd = 1.f / sqrtf(wave_sum(s2) * (1.f / DM) + 1e-5f);
;             const int b = row / SEQ;
; #pragma unroll
;             for (int j = 0; j < 4; ++j) { const f32x4 c = *((const f32x4*)(msc + b * 6144) + lane + 64 * j), h = *((const f32x4*)(msh + b * 6144) + lane + 64 * j);
;                 const f32x4 w = v[j] * rstd * (c + 1.f) + h;
;                 u32x2 o; o.x = pk2(w.x, w.y); o.y = pk2(w.z, w.w);
;                 *((u32x2*)(Hout + (size_t)row * DM) + lane + 64 * j) = o; }
	v_mov_b64_e32 v[4:5], v[128:129]
	v_mov_b64_e32 v[6:7], v[130:131]
	v_mov_b64_e32 v[8:9], v[132:133]
	v_mov_b64_e32 v[10:11], v[134:135]
	v_pk_add_f32 v[4:5], v[4:5], 1.0 op_sel_hi:[1,0]
	v_pk_add_f32 v[42:43], v[42:43], v[46:47]
	v_pk_add_f32 v[6:7], v[6:7], 1.0 op_sel_hi:[1,0]
	v_add_f32_e32 v27, v42, v43
	v_mov_b32_e32 v32, v27
	s_nop 1
	v_mov_b32_dpp v32, v32 quad_perm:[1,0,3,2] row_mask:0xf bank_mask:0xf
	v_add_f32_e32 v27, v27, v32
	v_mov_b32_e32 v32, v27
	s_nop 1
	v_mov_b32_dpp v32, v32 quad_perm:[2,3,0,1] row_mask:0xf bank_mask:0xf
	v_add_f32_e32 v27, v27, v32
	v_mov_b32_e32 v32, v27
	s_nop 1
	v_mov_b32_dpp v32, v32 row_half_mirror row_mask:0xf bank_mask:0xf
	v_add_f32_e32 v27, v27, v32
	v_mov_b32_e32 v32, v27
	s_nop 1
	v_mov_b32_dpp v32, v32 row_mirror row_mask:0xf bank_mask:0xf
	v_add_f32_e32 v27, v27, v32
	s_nop 0
	v_readlane_b32 s22, v27, 16
	v_readlane_b32 s23, v27, 48
	v_readlane_b32 s0, v27, 0
	v_readlane_b32 s1, v27, 32
	v_mov_b32_e32 v42, s22
	v_mov_b32_e32 v43, s23
	v_pk_add_f32 v[42:43], s[0:1], v[42:43]
	s_nop 0
	v_add_f32_e32 v27, v42, v43
	v_fmamk_f32 v13, v27, 0xba800000, v13
	v_fmac_f32_e32 v12, 0xba800000, v27
	v_fmamk_f32 v15, v27, 0xba800000, v15
	v_fmac_f32_e32 v14, 0xba800000, v27
	v_fmamk_f32 v37, v27, 0xba800000, v37
	v_fmac_f32_e32 v36, 0xba800000, v27
	v_fmamk_f32 v35, v27, 0xba800000, v35
	v_fmac_f32_e32 v34, 0xba800000, v27
	v_pk_mul_f32 v[42:43], v[14:15], v[14:15]
	v_pk_mul_f32 v[44:45], v[12:13], v[12:13]
	v_pk_mul_f32 v[46:47], v[34:35], v[34:35]
	v_pk_mul_f32 v[48:49], v[36:37], v[36:37]
	v_fmac_f32_e32 v40, 0xba800000, v27
	v_fmac_f32_e32 v38, 0xba800000, v27
	v_pk_mov_b32 v[52:53], v[44:45], v[42:43] op_sel:[1,0]
	v_mov_b32_e32 v45, v43
	v_pk_mov_b32 v[42:43], v[48:49], v[46:47] op_sel:[1,0]
	v_mov_b32_e32 v49, v47
	v_fmamk_f32 v41, v27, 0xba800000, v41
	v_fmamk_f32 v39, v27, 0xba800000, v39
	v_mul_f32_e32 v32, v40, v40
	v_mul_f32_e32 v50, v38, v38
	v_pk_add_f32 v[44:45], v[52:53], v[44:45]
	v_pk_add_f32 v[42:43], v[42:43], v[48:49]
	v_fmamk_f32 v1, v27, 0xba800000, v1
	v_fmac_f32_e32 v0, 0xba800000, v27
	v_fmamk_f32 v3, v27, 0xba800000, v3
	v_fmac_f32_e32 v2, 0xba800000, v27
	v_pk_fma_f32 v[46:47], v[40:41], v[40:41], v[32:33] op_sel_hi:[1,1,0]
	v_pk_fma_f32 v[50:51], v[38:39], v[38:39], v[50:51] op_sel_hi:[1,1,0]
	v_pk_add_f32 v[44:45], v[44:45], v[44:45] op_sel_hi:[0,1]
	v_pk_add_f32 v[42:43], v[42:43], v[42:43] op_sel_hi:[0,1]
	v_mul_f32_e32 v46, v2, v2
	v_mul_f32_e32 v50, v3, v3
	v_mul_f32_e32 v44, v0, v0
	v_mul_f32_e32 v42, v1, v1
	v_pk_add_f32 v[46:47], v[46:47], v[50:51]
	v_pk_add_f32 v[42:43], v[44:45], v[42:43]
	s_nop 0
	v_pk_add_f32 v[42:43], v[46:47], v[42:43]
	s_nop 0
	v_add_f32_e32 v27, v42, v43
	v_mov_b32_e32 v32, v27
	s_nop 1
	v_mov_b32_dpp v32, v32 quad_perm:[1,0,3,2] row_mask:0xf bank_mask:0xf
	v_add_f32_e32 v27, v27, v32
	v_mov_b32_e32 v32, v27
	s_nop 1
	v_mov_b32_dpp v32, v32 quad_perm:[2,3,0,1] row_mask:0xf bank_mask:0xf
	v_add_f32_e32 v27, v27, v32
	v_mov_b32_e32 v32, v27
	s_nop 1
	v_mov_b32_dpp v32, v32 row_half_mirror row_mask:0xf bank_mask:0xf
	v_add_f32_e32 v27, v27, v32
	v_mov_b32_e32 v32, v27
	s_nop 1
	v_mov_b32_dpp v32, v32 row_mirror row_mask:0xf bank_mask:0xf
	v_add_f32_e32 v27, v27, v32
	s_nop 0
	v_readlane_b32 s22, v27, 16
	v_readlane_b32 s23, v27, 48
	v_readlane_b32 s0, v27, 0
	v_readlane_b32 s1, v27, 32
	v_mov_b32_e32 v42, s22
	v_mov_b32_e32 v43, s23
	v_pk_add_f32 v[42:43], s[0:1], v[42:43]
	s_nop 0
	v_add_f32_e32 v27, v42, v43
	v_fmamk_f32 v27, v27, 0x3a800000, v17
	v_mul_f32_e32 v32, 0x4f800000, v27
	v_cmp_gt_f32_e32 vcc, s7, v27
	s_nop 1
	v_cndmask_b32_e32 v27, v27, v32, vcc
	v_sqrt_f32_e32 v32, v27
	s_nop 0
	v_add_u32_e32 v42, -1, v32
	v_fma_f32 v43, -v42, v32, v27
	v_cmp_ge_f32_e64 s[0:1], 0, v43
	v_add_u32_e32 v43, 1, v32
	s_nop 0
	v_cndmask_b32_e64 v42, v32, v42, s[0:1]
	v_fma_f32 v32, -v43, v32, v27
	v_cmp_lt_f32_e64 s[0:1], 0, v32
	s_nop 1
	v_cndmask_b32_e64 v32, v42, v43, s[0:1]
	v_mul_f32_e32 v42, 0x37800000, v32
	v_cndmask_b32_e32 v32, v32, v42, vcc
	v_cmp_class_f32_e32 vcc, v27, v33
	s_nop 1
	v_cndmask_b32_e32 v27, v32, v27, vcc
	v_div_scale_f32 v32, s[0:1], v27, v27, 1.0
	v_rcp_f32_e32 v42, v32
	s_nop 0
	v_fma_f32 v43, -v32, v42, 1.0
	v_fmac_f32_e32 v42, v43, v42
	v_div_scale_f32 v43, vcc, 1.0, v27, 1.0
	v_mul_f32_e32 v44, v43, v42
	v_fma_f32 v45, -v32, v44, v43
	v_fmac_f32_e32 v44, v45, v42
	v_fma_f32 v32, -v32, v44, v43
	v_div_fmas_f32 v32, v32, v42, v44
	v_div_fixup_f32 v32, v32, v27, 1.0
	v_pk_mul_f32 v[12:13], v[12:13], v[32:33] op_sel_hi:[1,0]
	v_pk_mul_f32 v[14:15], v[14:15], v[32:33] op_sel_hi:[1,0]
	v_pk_fma_f32 v[4:5], v[4:5], v[12:13], v[8:9]
	v_pk_fma_f32 v[6:7], v[6:7], v[14:15], v[10:11]
	v_bfe_u32 v8, v4, 16, 1
	v_add3_u32 v4, v4, v8, s9
	v_bfe_u32 v8, v5, 16, 1
	v_lshrrev_b32_e32 v4, 16, v4
	v_add3_u32 v5, v5, v8, s9
	v_and_or_b32 v4, v5, s13, v4
	v_bfe_u32 v5, v6, 16, 1
	v_add3_u32 v5, v6, v5, s9
	v_bfe_u32 v6, v7, 16, 1
	v_lshrrev_b32_e32 v5, 16, v5
	v_add3_u32 v6, v7, v6, s9
	v_and_or_b32 v5, v6, s13, v5
	global_store_dwordx2 v[28:29], v[4:5], off
	s_nop 0
	v_mov_b64_e32 v[4:5], v[136:137]
	v_mov_b64_e32 v[6:7], v[138:139]
	v_mov_b64_e32 v[8:9], v[140:141]
	v_mov_b64_e32 v[10:11], v[142:143]
	v_pk_mul_f32 v[12:13], v[36:37], v[32:33] op_sel_hi:[1,0]
	v_pk_mul_f32 v[14:15], v[34:35], v[32:33] op_sel_hi:[1,0]
	v_pk_mul_f32 v[2:3], v[2:3], v[32:33] op_sel_hi:[1,0]
	v_pk_mul_f32 v[0:1], v[0:1], v[32:33] op_sel_hi:[1,0]
	v_cmp_le_i32_e32 vcc, s66, v16
	s_or_b64 s[20:21], vcc, s[20:21]
	v_pk_add_f32 v[6:7], v[6:7], 1.0 op_sel_hi:[1,0]
	v_pk_add_f32 v[4:5], v[4:5], 1.0 op_sel_hi:[1,0]
	v_pk_fma_f32 v[6:7], v[6:7], v[14:15], v[10:11]
; __device__ __forceinline__ unsigned pk2(float lo, float hi) { return f2bf(lo) | (f2bf(hi) << 16); }
; __device__ __forceinline__ void ln_pass(const float* src, float* dstx, const float* lg, const float* lb, const float* msc, const float* msh, bf16_t* Hout, float* statout, const LnRows R) {
;     ...
;             for (int j = 0; j < 4; ++j) { const f32x4 c = *((const f32x4*)(msc + b * 6144) + lane + 64 * j), h = *((const f32x4*)(msh + b * 6144) + lane + 64 * j);
;                 const f32x4 w = v[j] * rstd * (c + 1.f) + h;
;                 u32x2 o; o.x = pk2(w.x, w.y); o.y = pk2(w.z, w.w);
;                 *((u32x2*)(Hout + (size_t)row * DM) + lane + 64 * j) = o; }
	v_pk_fma_f32 v[4:5], v[4:5], v[12:13], v[8:9]
	v_bfe_u32 v10, v6, 16, 1
	v_bfe_u32 v8, v4, 16, 1
	v_bfe_u32 v9, v5, 16, 1
	v_bfe_u32 v11, v7, 16, 1
	v_add3_u32 v4, v4, v8, s9
	v_add3_u32 v6, v6, v10, s9
	v_add3_u32 v5, v5, v9, s9
	v_add3_u32 v7, v7, v11, s9
	v_lshrrev_b32_e32 v4, 16, v4
	v_lshrrev_b32_e32 v6, 16, v6
	v_and_or_b32 v4, v5, s13, v4
	v_and_or_b32 v5, v7, s13, v6
	global_store_dwordx2 v[28:29], v[4:5], off offset:512
	s_nop 0
	v_mov_b64_e32 v[4:5], v[144:145]
	v_mov_b64_e32 v[6:7], v[146:147]
	v_mov_b64_e32 v[8:9], v[148:149]
	v_mov_b64_e32 v[10:11], v[150:151]
	v_pk_mul_f32 v[12:13], v[40:41], v[32:33] op_sel_hi:[1,0]
	v_pk_mul_f32 v[14:15], v[38:39], v[32:33] op_sel_hi:[1,0]
	v_pk_add_f32 v[6:7], v[6:7], 1.0 op_sel_hi:[1,0]
	v_pk_add_f32 v[4:5], v[4:5], 1.0 op_sel_hi:[1,0]
	v_pk_fma_f32 v[6:7], v[6:7], v[14:15], v[10:11]
	v_pk_fma_f32 v[4:5], v[4:5], v[12:13], v[8:9]
	v_bfe_u32 v10, v6, 16, 1
	v_bfe_u32 v8, v4, 16, 1
	v_bfe_u32 v9, v5, 16, 1
	v_bfe_u32 v11, v7, 16, 1
	v_add3_u32 v4, v4, v8, s9
	v_add3_u32 v6, v6, v10, s9
	v_add3_u32 v5, v5, v9, s9
	v_add3_u32 v7, v7, v11, s9
	v_lshrrev_b32_e32 v4, 16, v4
	v_lshrrev_b32_e32 v6, 16, v6
	v_and_or_b32 v4, v5, s13, v4
	v_and_or_b32 v5, v7, s13, v6
	global_store_dwordx2 v[28:29], v[4:5], off offset:1024
	s_nop 0
	v_mov_b64_e32 v[4:5], v[152:153]
	v_mov_b64_e32 v[6:7], v[154:155]
	v_mov_b64_e32 v[8:9], v[156:157]
	v_mov_b64_e32 v[10:11], v[158:159]
	v_pk_add_f32 v[6:7], v[6:7], 1.0 op_sel_hi:[1,0]
	v_pk_add_f32 v[4:5], v[4:5], 1.0 op_sel_hi:[1,0]
	v_pk_fma_f32 v[0:1], v[0:1], v[6:7], v[10:11]
	v_pk_fma_f32 v[2:3], v[2:3], v[4:5], v[8:9]
	v_bfe_u32 v6, v0, 16, 1
	v_bfe_u32 v4, v2, 16, 1
	v_bfe_u32 v5, v3, 16, 1
	v_bfe_u32 v7, v1, 16, 1
	v_add3_u32 v2, v2, v4, s9
	v_add3_u32 v0, v0, v6, s9
	v_add3_u32 v3, v3, v5, s9
	v_add3_u32 v1, v1, v7, s9
	v_lshrrev_b32_e32 v2, 16, v2
	v_lshrrev_b32_e32 v4, 16, v0
	v_and_or_b32 v0, v3, s13, v2
	v_and_or_b32 v1, v1, s13, v4
	global_store_dwordx2 v[28:29], v[0:1], off offset:1536
	v_lshl_add_u64 v[28:29], v[28:29], 0, s[16:17]
	s_andn2_b64 exec, exec, s[20:21]
	s_cbranch_execz .LBB0_1536
; __device__ __forceinline__ void ln_pass(const float* src, float* dstx, const float* lg, const float* lb, const float* msc, const float* msh, bf16_t* Hout, float* statout, const LnRows R) {
;     ...
;     for (int row = R.rbase + R.gw; row < R.rend; row += R.ngw) {
;         const f32x4* xr = (const f32x4*)(src + (size_t)row * DM) + lane;
;         f32x4 v[4];
; #pragma unroll
;         for (int j = 0; j < 4; ++j) v[j] = xr[64 * j];
;         if (lg) {
;             float s = 0.f;
; #pragma unroll
;             for (int j = 0; j < 4; ++j) s += (v[j].x + v[j].y) + (v[j].z + v[j].w);
;             const float mean = wave_sum(s) * (1.f / DM); float s2 = 0.f;
; #pragma unroll
;             for (int j = 0; j < 4; ++j) { v[j] = v[j] - mean; s2 += (v[j].x * v[j].x + v[j].y * v[j].y) + (v[j].z * v[j].z + v[j].w * v[j].w); }
;             const float rstd = 1.f / sqrtf(wave_sum(s2) * (1.f / DM) + 1e-5f);
;             if (statout && lane == 0) { statout[2 * row] = mean; statout[2 * row + 1] = rstd; }
;     ...
;             const int b = row / SEQ;
; #pragma unroll
;             for (int j = 0; j < 4; ++j) { const f32x4 c = *((const f32x4*)(msc + b * 6144) + lane + 64 * j), h = *((const f32x4*)(msh + b * 6144) + lane + 64 * j);
.LBB0_1534:
	global_load_dwordx4 v[12:15], v[30:31], off offset:-3072
	global_load_dwordx4 v[8:11], v[30:31], off offset:-2048
	global_load_dwordx4 v[4:7], v[30:31], off offset:-1024
	global_load_dwordx4 v[0:3], v[30:31], off
	v_ashrrev_i32_e32 v160, 31, v16
	v_lshrrev_b32_e32 v160, 19, v160
	v_add_u32_e32 v160, v16, v160
	v_ashrrev_i32_e32 v160, 13, v160
	v_mul_i32_i24_e32 v160, 0x1800, v160
	v_ashrrev_i32_e32 v161, 31, v160
	v_lshlrev_b64 v[160:161], 2, v[160:161]
	v_lshl_add_u64 v[162:163], v[22:23], 0, v[160:161]
	v_lshl_add_u64 v[164:165], v[24:25], 0, v[160:161]
	global_load_dwordx4 v[128:131], v[162:163], off
	global_load_dwordx4 v[132:135], v[164:165], off
	global_load_dwordx4 v[136:139], v[162:163], off offset:1024
	global_load_dwordx4 v[140:143], v[164:165], off offset:1024
	global_load_dwordx4 v[144:147], v[162:163], off offset:2048
	global_load_dwordx4 v[148:151], v[164:165], off offset:2048
	global_load_dwordx4 v[152:155], v[162:163], off offset:3072
	global_load_dwordx4 v[156:159], v[164:165], off offset:3072
	s_waitcnt vmcnt(8)
	v_mov_b32_e32 v34, v13
	v_mov_b32_e32 v35, v14
	v_mov_b32_e32 v36, v12
	v_mov_b32_e32 v37, v15
	v_mov_b32_e32 v38, v9
	v_mov_b32_e32 v39, v10
	v_mov_b32_e32 v40, v8
	v_mov_b32_e32 v41, v11
	v_pk_add_f32 v[34:35], v[34:35], v[36:37]
	v_pk_add_f32 v[36:37], v[38:39], v[40:41]
	v_add_f32_e32 v27, v34, v35
	v_pk_add_f32 v[34:35], v[36:37], v[36:37] op_sel:[0,1] op_sel_hi:[1,0]
	v_add_f32_e32 v42, v4, v5
	v_add_f32_e32 v44, v6, v7
	v_mov_b32_e32 v47, v0
	v_mov_b32_e32 v43, v2
	v_mov_b32_e32 v45, v3
	v_add_f32_e32 v46, 0, v27
	v_mov_b32_e32 v35, v1
	v_pk_add_f32 v[38:39], v[42:43], v[44:45]
	v_pk_add_f32 v[34:35], v[46:47], v[34:35]
	s_nop 0
	v_pk_add_f32 v[34:35], v[34:35], v[38:39]
	s_nop 0
	v_add_f32_e32 v27, v34, v35
	v_mov_b32_e32 v32, v27
	s_nop 1
	v_mov_b32_dpp v32, v32 quad_perm:[1,0,3,2] row_mask:0xf bank_mask:0xf
	v_add_f32_e32 v27, v27, v32
	v_mov_b32_e32 v32, v27
	s_nop 1
	v_mov_b32_dpp v32, v32 quad_perm:[2,3,0,1] row_mask:0xf bank_mask:0xf
	v_add_f32_e32 v27, v27, v32
	v_mov_b32_e32 v32, v27
	s_nop 1
	v_mov_b32_dpp v32, v32 row_half_mirror row_mask:0xf bank_mask:0xf
	v_add_f32_e32 v27, v27, v32
	v_mov_b32_e32 v32, v27
	s_nop 1
	v_mov_b32_dpp v32, v32 row_mirror row_mask:0xf bank_mask:0xf
	v_add_f32_e32 v27, v27, v32
	s_nop 0
	v_readlane_b32 s22, v27, 16
	v_readlane_b32 s23, v27, 48
	v_readlane_b32 s0, v27, 0
	v_readlane_b32 s1, v27, 32
	v_mov_b32_e32 v34, s22
	v_mov_b32_e32 v35, s23
	v_pk_add_f32 v[34:35], s[0:1], v[34:35]
	s_nop 0
	v_add_f32_e32 v27, v34, v35
	v_fmamk_f32 v15, v27, 0xba800000, v15
	v_fmamk_f32 v13, v27, 0xba800000, v13
	v_fmamk_f32 v11, v27, 0xba800000, v11
	v_fmamk_f32 v9, v27, 0xba800000, v9
	v_fmamk_f32 v14, v27, 0xba800000, v14
	v_fmac_f32_e32 v12, 0xba800000, v27
	v_fmamk_f32 v10, v27, 0xba800000, v10
	v_fmac_f32_e32 v8, 0xba800000, v27
	v_fmamk_f32 v7, v27, 0xba800000, v7
	v_fmamk_f32 v5, v27, 0xba800000, v5
	v_mul_f32_e32 v32, v13, v13
	v_mul_f32_e32 v34, v15, v15
	v_mul_f32_e32 v35, v9, v9
	v_mul_f32_e32 v36, v11, v11
	v_fmamk_f32 v6, v27, 0xba800000, v6
	v_fmac_f32_e32 v4, 0xba800000, v27
	v_fmamk_f32 v3, v27, 0xba800000, v3
	v_fmamk_f32 v1, v27, 0xba800000, v1
	v_mul_f32_e32 v37, v5, v5
	v_mul_f32_e32 v38, v7, v7
	v_fmac_f32_e32 v32, v12, v12
	v_fmac_f32_e32 v34, v14, v14
	v_fmac_f32_e32 v35, v8, v8
	v_fmac_f32_e32 v36, v10, v10
	v_fmamk_f32 v2, v27, 0xba800000, v2
	v_fmac_f32_e32 v0, 0xba800000, v27
	v_mul_f32_e32 v39, v1, v1
	v_mul_f32_e32 v40, v3, v3
	v_fmac_f32_e32 v37, v4, v4
	v_fmac_f32_e32 v38, v6, v6
	v_add_f32_e32 v32, v32, v34
	v_add_f32_e32 v34, v35, v36
	v_fmac_f32_e32 v39, v0, v0
	v_fmac_f32_e32 v40, v2, v2
	v_add_f32_e32 v35, v37, v38
	v_add_f32_e32 v32, v32, v34
	v_add_f32_e32 v36, v39, v40
	v_add_f32_e32 v32, v35, v32
	v_add_f32_e32 v32, v36, v32
	v_mov_b32_e32 v34, v32
	s_nop 1
	v_mov_b32_dpp v34, v34 quad_perm:[1,0,3,2] row_mask:0xf bank_mask:0xf
	v_add_f32_e32 v32, v32, v34
	v_mov_b32_e32 v34, v32
	s_nop 1
	v_mov_b32_dpp v34, v34 quad_perm:[2,3,0,1] row_mask:0xf bank_mask:0xf
	v_add_f32_e32 v32, v32, v34
	v_mov_b32_e32 v34, v32
	s_nop 1
	v_mov_b32_dpp v34, v34 row_half_mirror row_mask:0xf bank_mask:0xf
	v_add_f32_e32 v32, v32, v34
	v_mov_b32_e32 v34, v32
	s_nop 1
	v_mov_b32_dpp v34, v34 row_mirror row_mask:0xf bank_mask:0xf
	v_add_f32_e32 v32, v32, v34
	s_nop 0
	v_readlane_b32 s1, v32, 16
	v_readlane_b32 s23, v32, 48
	v_readlane_b32 s0, v32, 0
	v_readlane_b32 s22, v32, 32
	v_mov_b32_e32 v32, s1
	v_mov_b32_e32 v34, s23
	v_add_f32_e32 v32, s0, v32
	v_add_f32_e32 v34, s22, v34
	v_add_f32_e32 v32, v32, v34
	v_fmamk_f32 v32, v32, 0x3a800000, v17
	v_mul_f32_e32 v34, 0x4f800000, v32
	v_cmp_gt_f32_e32 vcc, s7, v32
	s_nop 1
	v_cndmask_b32_e32 v32, v32, v34, vcc
	v_sqrt_f32_e32 v34, v32
	s_nop 0
	v_add_u32_e32 v35, -1, v34
	v_add_u32_e32 v36, 1, v34
	v_fma_f32 v37, -v35, v34, v32
	v_fma_f32 v38, -v36, v34, v32
	v_cmp_ge_f32_e64 s[0:1], 0, v37
	s_nop 1
	v_cndmask_b32_e64 v34, v34, v35, s[0:1]
	v_cmp_lt_f32_e64 s[0:1], 0, v38
	s_nop 1
	v_cndmask_b32_e64 v34, v34, v36, s[0:1]
	v_mul_f32_e32 v35, 0x37800000, v34
	v_cndmask_b32_e32 v34, v34, v35, vcc
	v_cmp_class_f32_e32 vcc, v32, v33
	s_nop 1
	v_cndmask_b32_e32 v32, v34, v32, vcc
	v_div_scale_f32 v34, s[0:1], v32, v32, 1.0
	v_rcp_f32_e32 v35, v34
	v_div_scale_f32 v36, vcc, 1.0, v32, 1.0
	v_fma_f32 v37, -v34, v35, 1.0
	v_fmac_f32_e32 v35, v37, v35
	v_mul_f32_e32 v37, v36, v35
	v_fma_f32 v38, -v34, v37, v36
	v_fmac_f32_e32 v37, v38, v35
	v_fma_f32 v34, -v34, v37, v36
	v_div_fmas_f32 v34, v34, v35, v37
	v_div_fixup_f32 v32, v34, v32, 1.0
	s_and_saveexec_b64 s[0:1], s[2:3]
	s_cbranch_execz .LBB0_1533
	v_mul_f32_e32 v34, 0x3a800000, v27
	v_ashrrev_i32_e32 v27, 31, v26
	v_lshl_add_u64 v[36:37], v[26:27], 2, s[14:15]
	v_mov_b32_e32 v35, v32
	global_store_dwordx2 v[36:37], v[34:35], off
	s_branch .LBB0_1533

; __device__ __forceinline__ void ln_pass(const float* src, float* dstx, const float* lg, const float* lb, const float* msc, const float* msh, bf16_t* Hout, float* statout, const LnRows R) {
;     const int lane = threadIdx.x & 63;
;     for (int row = R.rbase + R.gw; row < R.rend; row += R.ngw) {
;         const f32x4* xr = (const f32x4*)(src + (size_t)row * DM) + lane;
;         f32x4 v[4];
; #pragma unroll
;         for (int j = 0; j < 4; ++j) v[j] = xr[64 * j];
;         if (lg) {
;             float s = 0.f;
; #pragma unroll
;             for (int j = 0; j < 4; ++j) s += (v[j].x + v[j].y) + (v[j].z + v[j].w);
;             const float mean = wave_sum(s) * (1.f / DM); float s2 = 0.f;
; #pragma unroll
;             for (int j = 0; j < 4; ++j) { v[j] = v[j] - mean; s2 += (v[j].x * v[j].x + v[j].y * v[j].y) + (v[j].z * v[j].z + v[j].w * v[j].w); }
;             const float rstd = 1.f / sqrtf(wave_sum(s2) * (1.f / DM) + 1e-5f);
;             if (statout && lane == 0) { statout[2 * row] = mean; statout[2 * row + 1] = rstd; }
; #pragma unroll
;             for (int j = 0; j < 4; ++j) { const f32x4 g = *((const f32x4*)lg + lane + 64 * j), b = *((const f32x4*)lb + lane + 64 * j); v[j] = v[j] * rstd * g + b;
;                 if (dstx) *((f32x4*)(dstx + (size_t)row * DM) + lane + 64 * j) = v[j]; }
;         }
; template <int ph>
; __device__ __forceinline__ void run_phase(const Params& p, unsigned char* lds, const int vc, const LnRows lnl) {
;     ...
;                 ln_pass(X, nullptr, p.in[I_LNG] + (l * 2 + 0) * DM, p.in[I_LNB] + (l * 2 + 0) * DM, modl + 4 * 1024, modl + 3 * 1024, Hb, (float*)(ws + WS_STAT), lnl);
.LBB0_2626:
	s_cmp_lt_i32 s4, 21
	s_cselect_b64 s[0:1], -1, 0
	s_cmp_gt_i32 s5, 20
	s_cselect_b64 s[2:3], -1, 0
	s_and_b64 s[0:1], s[0:1], s[2:3]
	s_andn2_b64 vcc, exec, s[0:1]
	s_cbranch_vccnz .LBB0_2711
	v_add_u32_e32 v16, s90, v193
	v_cmp_gt_i32_e32 vcc, s66, v16
	s_and_saveexec_b64 s[4:5], vcc
	s_cbranch_execz .LBB0_2632
	v_and_b32_e32 v4, 63, v192
	v_readlane_b32 s16, v246, 0
	v_lshlrev_b32_e32 v0, 4, v4
	v_mov_b32_e32 v1, 0
	v_readlane_b32 s22, v246, 6
	v_readlane_b32 s23, v246, 7
	s_mov_b64 s[0:1], 0x2000
	v_ashrrev_i32_e32 v17, 31, v16
	v_lshl_add_u64 v[2:3], s[22:23], 0, v[0:1]
	v_lshl_add_u64 v[18:19], v[2:3], 0, s[0:1]
	v_lshl_add_u64 v[2:3], s[92:93], 0, v[0:1]
	v_lshl_add_u64 v[20:21], v[2:3], 0, s[0:1]
	v_lshl_add_u64 v[2:3], s[96:97], 0, v[0:1]
	s_mov_b64 s[0:1], 0x1c000
	v_lshl_add_u64 v[22:23], v[2:3], 0, s[0:1]
	s_mov_b64 s[0:1], 0x1b000
	v_lshl_add_u64 v[24:25], v[2:3], 0, s[0:1]
	v_lshlrev_b64 v[2:3], 11, v[16:17]
	v_lshl_or_b32 v2, v4, 3, v2
	v_lshl_add_u64 v[2:3], s[96:97], 0, v[2:3]
	s_mov_b64 s[0:1], 0x4c00000
	v_lshl_add_u64 v[28:29], v[2:3], 0, s[0:1]
	v_lshlrev_b64 v[2:3], 12, v[16:17]
	s_add_u32 s12, s96, 0x600000
	v_or_b32_e32 v2, v2, v0
	s_addc_u32 s13, s97, 0
	v_readlane_b32 s17, v246, 1
	v_readlane_b32 s18, v246, 2
	v_readlane_b32 s19, v246, 3
	v_readlane_b32 s20, v246, 4
	s_ashr_i32 s9, s8, 31
	v_lshl_add_u64 v[0:1], s[94:95], 0, v[2:3]
	s_mov_b64 s[0:1], 0xc00
	v_cmp_eq_u32_e64 s[2:3], 0, v4
	v_lshlrev_b32_e32 v26, 1, v16
	s_lshl_b32 s6, s8, 1
	s_lshl_b64 s[14:15], s[8:9], 11
	v_lshl_add_u64 v[30:31], v[0:1], 0, s[0:1]
	s_lshl_b64 s[16:17], s[8:9], 12
	s_mov_b64 s[18:19], 0
	v_mov_b32_e32 v17, 0x3727c5ac
	s_mov_b32 s7, 0xf800000
	v_mov_b32_e32 v33, 0x260
	s_movk_i32 s9, 0x7fff
	s_mov_b32 s20, 0xffff0000
	v_readlane_b32 s21, v246, 5
	global_load_dwordx4 v[96:99], v[20:21], off
	global_load_dwordx4 v[100:103], v[18:19], off
	global_load_dwordx4 v[104:107], v[18:19], off offset:1024
	global_load_dwordx4 v[108:111], v[20:21], off offset:1024
	global_load_dwordx4 v[112:115], v[20:21], off offset:2048
	global_load_dwordx4 v[116:119], v[18:19], off offset:2048
	global_load_dwordx4 v[120:123], v[18:19], off offset:3072
	global_load_dwordx4 v[124:127], v[20:21], off offset:3072
	s_branch .LBB0_2630
.LBB0_2629:
	s_or_b64 exec, exec, s[0:1]
	v_mov_b64_e32 v[34:35], v[96:97]
	v_mov_b64_e32 v[36:37], v[98:99]
	v_mov_b64_e32 v[38:39], v[100:101]
	v_mov_b64_e32 v[40:41], v[102:103]
	v_mov_b64_e32 v[42:43], v[104:105]
	v_mov_b64_e32 v[44:45], v[106:107]
	v_mov_b64_e32 v[46:47], v[108:109]
	v_mov_b64_e32 v[48:49], v[110:111]
	v_mov_b64_e32 v[50:51], v[112:113]
	v_mov_b64_e32 v[52:53], v[114:115]
	v_mov_b64_e32 v[54:55], v[116:117]
	v_mov_b64_e32 v[56:57], v[118:119]
	v_mov_b64_e32 v[58:59], v[120:121]
	v_mov_b64_e32 v[60:61], v[122:123]
	v_mov_b64_e32 v[62:63], v[124:125]
	v_mov_b64_e32 v[64:65], v[126:127]
	v_pk_mul_f32 v[74:75], v[0:1], v[32:33] op_sel_hi:[1,0]
	v_ashrrev_i32_e32 v0, 31, v16
	v_lshrrev_b32_e32 v0, 19, v0
	v_add_u32_e32 v0, v16, v0
	v_ashrrev_i32_e32 v0, 13, v0
	v_mul_i32_i24_e32 v0, 0x1800, v0
	v_ashrrev_i32_e32 v1, 31, v0
	v_lshlrev_b64 v[0:1], 2, v[0:1]
	v_lshl_add_u64 v[76:77], v[22:23], 0, v[0:1]
	v_pk_mul_f32 v[14:15], v[14:15], v[32:33] op_sel_hi:[1,0]
	v_pk_mul_f32 v[12:13], v[12:13], v[32:33] op_sel_hi:[1,0]
	v_pk_mul_f32 v[66:67], v[10:11], v[32:33] op_sel_hi:[1,0]
	v_pk_mul_f32 v[68:69], v[8:9], v[32:33] op_sel_hi:[1,0]
	v_pk_mul_f32 v[70:71], v[6:7], v[32:33] op_sel_hi:[1,0]
	v_pk_mul_f32 v[72:73], v[4:5], v[32:33] op_sel_hi:[1,0]
	v_lshl_add_u64 v[78:79], v[24:25], 0, v[0:1]
	v_pk_mul_f32 v[2:3], v[2:3], v[32:33] op_sel_hi:[1,0]
	v_add_u32_e32 v16, s8, v16
	v_add_u32_e32 v26, s6, v26
	v_lshl_add_u64 v[30:31], v[30:31], 0, s[16:17]
	v_pk_fma_f32 v[14:15], v[14:15], v[40:41], v[36:37]
	v_pk_fma_f32 v[12:13], v[12:13], v[38:39], v[34:35]
	v_pk_fma_f32 v[34:35], v[66:67], v[44:45], v[48:49]
	v_pk_fma_f32 v[36:37], v[68:69], v[42:43], v[46:47]
	v_pk_mov_b32 v[42:43], v[12:13], v[14:15] op_sel:[1,0]
	v_mov_b32_e32 v44, v12
	v_mov_b32_e32 v45, v15
	v_pk_mov_b32 v[46:47], v[36:37], v[34:35] op_sel:[1,0]
	v_mov_b32_e32 v48, v36
	v_mov_b32_e32 v49, v35
	v_pk_add_f32 v[42:43], v[42:43], v[44:45]
	v_pk_add_f32 v[44:45], v[46:47], v[48:49]
	v_pk_fma_f32 v[38:39], v[70:71], v[56:57], v[52:53]
	v_pk_fma_f32 v[40:41], v[72:73], v[54:55], v[50:51]
	v_pk_fma_f32 v[0:1], v[2:3], v[60:61], v[64:65]
	v_pk_fma_f32 v[2:3], v[74:75], v[58:59], v[62:63]
	v_add_f32_e32 v27, v42, v43
	v_pk_add_f32 v[42:43], v[44:45], v[44:45] op_sel:[0,1] op_sel_hi:[1,0]
	v_add_f32_e32 v50, v40, v41
	v_add_f32_e32 v52, v38, v39
	v_mov_b32_e32 v55, v2
	v_mov_b32_e32 v51, v0
	v_mov_b32_e32 v53, v1
	v_add_f32_e32 v54, 0, v27
	v_mov_b32_e32 v43, v3
	v_pk_add_f32 v[46:47], v[50:51], v[52:53]
	v_pk_add_f32 v[42:43], v[54:55], v[42:43]
	s_waitcnt vmcnt(0)
; __device__ __forceinline__ unsigned pk2(float lo, float hi) { return f2bf(lo) | (f2bf(hi) << 16); }
; __device__ __forceinline__ void ln_pass(const float* src, float* dstx, const float* lg, const float* lb, const float* msc, const float* msh, bf16_t* Hout, float* statout, const LnRows R) {
;     ...
;         if (Hout) {
;             float s = 0.f;
; #pragma unroll
;             for (int j = 0; j < 4; ++j) s += (v[j].x + v[j].y) + (v[j].z + v[j].w);
;             const float mean = wave_sum(s) * (1.f / DM); float s2 = 0.f;
; #pragma unroll
;             for (int j = 0; j < 4; ++j) { v[j] = v[j] - mean; s2 += (v[j].x * v[j].x + v[j].y * v[j].y) + (v[j].z * v[j].z + v[j].w * v[j].w); }
;             const float rstd = 1.f / sqrtf(wave_sum(s2) * (1.f / DM) + 1e-5f);
;             const int b = row / SEQ;
; #pragma unroll
;             for (int j = 0; j < 4; ++j) { const f32x4 c = *((const f32x4*)(msc + b * 6144) + lane + 64 * j), h = *((const f32x4*)(msh + b * 6144) + lane + 64 * j);
;                 const f32x4 w = v[j] * rstd * (c + 1.f) + h;
;                 u32x2 o; o.x = pk2(w.x, w.y); o.y = pk2(w.z, w.w);
;                 *((u32x2*)(Hout + (size_t)row * DM) + lane + 64 * j) = o; }
	v_mov_b64_e32 v[4:5], v[128:129]
	v_mov_b64_e32 v[6:7], v[130:131]
	v_mov_b64_e32 v[8:9], v[132:133]
	v_mov_b64_e32 v[10:11], v[134:135]
	v_pk_add_f32 v[4:5], v[4:5], 1.0 op_sel_hi:[1,0]
	v_pk_add_f32 v[42:43], v[42:43], v[46:47]
	v_pk_add_f32 v[6:7], v[6:7], 1.0 op_sel_hi:[1,0]
	v_add_f32_e32 v27, v42, v43
	v_mov_b32_e32 v32, v27
	s_nop 1
	v_mov_b32_dpp v32, v32 quad_perm:[1,0,3,2] row_mask:0xf bank_mask:0xf
	v_add_f32_e32 v27, v27, v32
	v_mov_b32_e32 v32, v27
	s_nop 1
	v_mov_b32_dpp v32, v32 quad_perm:[2,3,0,1] row_mask:0xf bank_mask:0xf
	v_add_f32_e32 v27, v27, v32
	v_mov_b32_e32 v32, v27
	s_nop 1
	v_mov_b32_dpp v32, v32 row_half_mirror row_mask:0xf bank_mask:0xf
	v_add_f32_e32 v27, v27, v32
	v_mov_b32_e32 v32, v27
	s_nop 1
	v_mov_b32_dpp v32, v32 row_mirror row_mask:0xf bank_mask:0xf
	v_add_f32_e32 v27, v27, v32
	s_nop 0
	v_readlane_b32 s21, v27, 16
	v_readlane_b32 s22, v27, 48
	v_readlane_b32 s0, v27, 0
	v_readlane_b32 s1, v27, 32
	v_mov_b32_e32 v42, s21
	v_mov_b32_e32 v43, s22
	v_pk_add_f32 v[42:43], s[0:1], v[42:43]
	s_nop 0
	v_add_f32_e32 v27, v42, v43
	v_fmamk_f32 v13, v27, 0xba800000, v13
	v_fmac_f32_e32 v12, 0xba800000, v27
	v_fmamk_f32 v15, v27, 0xba800000, v15
	v_fmac_f32_e32 v14, 0xba800000, v27
	v_fmamk_f32 v37, v27, 0xba800000, v37
	v_fmac_f32_e32 v36, 0xba800000, v27
	v_fmamk_f32 v35, v27, 0xba800000, v35
	v_fmac_f32_e32 v34, 0xba800000, v27
	v_pk_mul_f32 v[42:43], v[14:15], v[14:15]
	v_pk_mul_f32 v[44:45], v[12:13], v[12:13]
	v_pk_mul_f32 v[46:47], v[34:35], v[34:35]
	v_pk_mul_f32 v[48:49], v[36:37], v[36:37]
	v_fmac_f32_e32 v40, 0xba800000, v27
	v_fmac_f32_e32 v38, 0xba800000, v27
	v_pk_mov_b32 v[52:53], v[44:45], v[42:43] op_sel:[1,0]
	v_mov_b32_e32 v45, v43
	v_pk_mov_b32 v[42:43], v[48:49], v[46:47] op_sel:[1,0]
	v_mov_b32_e32 v49, v47
	v_fmamk_f32 v41, v27, 0xba800000, v41
	v_fmamk_f32 v39, v27, 0xba800000, v39
	v_mul_f32_e32 v32, v40, v40
	v_mul_f32_e32 v50, v38, v38
	v_pk_add_f32 v[44:45], v[52:53], v[44:45]
	v_pk_add_f32 v[42:43], v[42:43], v[48:49]
	v_fmamk_f32 v1, v27, 0xba800000, v1
	v_fmac_f32_e32 v0, 0xba800000, v27
	v_fmamk_f32 v3, v27, 0xba800000, v3
	v_fmac_f32_e32 v2, 0xba800000, v27
	v_pk_fma_f32 v[46:47], v[40:41], v[40:41], v[32:33] op_sel_hi:[1,1,0]
	v_pk_fma_f32 v[50:51], v[38:39], v[38:39], v[50:51] op_sel_hi:[1,1,0]
	v_pk_add_f32 v[44:45], v[44:45], v[44:45] op_sel_hi:[0,1]
	v_pk_add_f32 v[42:43], v[42:43], v[42:43] op_sel_hi:[0,1]
	v_mul_f32_e32 v46, v2, v2
	v_mul_f32_e32 v50, v3, v3
	v_mul_f32_e32 v44, v0, v0
	v_mul_f32_e32 v42, v1, v1
	v_pk_add_f32 v[46:47], v[46:47], v[50:51]
	v_pk_add_f32 v[42:43], v[44:45], v[42:43]
	s_nop 0
	v_pk_add_f32 v[42:43], v[46:47], v[42:43]
	s_nop 0
	v_add_f32_e32 v27, v42, v43
	v_mov_b32_e32 v32, v27
	s_nop 1
	v_mov_b32_dpp v32, v32 quad_perm:[1,0,3,2] row_mask:0xf bank_mask:0xf
	v_add_f32_e32 v27, v27, v32
	v_mov_b32_e32 v32, v27
	s_nop 1
	v_mov_b32_dpp v32, v32 quad_perm:[2,3,0,1] row_mask:0xf bank_mask:0xf
	v_add_f32_e32 v27, v27, v32
	v_mov_b32_e32 v32, v27
	s_nop 1
	v_mov_b32_dpp v32, v32 row_half_mirror row_mask:0xf bank_mask:0xf
	v_add_f32_e32 v27, v27, v32
	v_mov_b32_e32 v32, v27
	s_nop 1
	v_mov_b32_dpp v32, v32 row_mirror row_mask:0xf bank_mask:0xf
	v_add_f32_e32 v27, v27, v32
	s_nop 0
	v_readlane_b32 s21, v27, 16
	v_readlane_b32 s22, v27, 48
	v_readlane_b32 s0, v27, 0
	v_readlane_b32 s1, v27, 32
	v_mov_b32_e32 v42, s21
	v_mov_b32_e32 v43, s22
	v_pk_add_f32 v[42:43], s[0:1], v[42:43]
	s_nop 0
	v_add_f32_e32 v27, v42, v43
	v_fmamk_f32 v27, v27, 0x3a800000, v17
	v_mul_f32_e32 v32, 0x4f800000, v27
	v_cmp_gt_f32_e32 vcc, s7, v27
	s_nop 1
	v_cndmask_b32_e32 v27, v27, v32, vcc
	v_sqrt_f32_e32 v32, v27
	s_nop 0
	v_add_u32_e32 v42, -1, v32
	v_fma_f32 v43, -v42, v32, v27
	v_cmp_ge_f32_e64 s[0:1], 0, v43
	v_add_u32_e32 v43, 1, v32
	s_nop 0
	v_cndmask_b32_e64 v42, v32, v42, s[0:1]
	v_fma_f32 v32, -v43, v32, v27
	v_cmp_lt_f32_e64 s[0:1], 0, v32
	s_nop 1
	v_cndmask_b32_e64 v32, v42, v43, s[0:1]
	v_mul_f32_e32 v42, 0x37800000, v32
	v_cndmask_b32_e32 v32, v32, v42, vcc
	v_cmp_class_f32_e32 vcc, v27, v33
	s_nop 1
	v_cndmask_b32_e32 v27, v32, v27, vcc
	v_div_scale_f32 v32, s[0:1], v27, v27, 1.0
	v_rcp_f32_e32 v42, v32
	s_nop 0
	v_fma_f32 v43, -v32, v42, 1.0
	v_fmac_f32_e32 v42, v43, v42
	v_div_scale_f32 v43, vcc, 1.0, v27, 1.0
	v_mul_f32_e32 v44, v43, v42
	v_fma_f32 v45, -v32, v44, v43
	v_fmac_f32_e32 v44, v45, v42
	v_fma_f32 v32, -v32, v44, v43
	v_div_fmas_f32 v32, v32, v42, v44
	v_div_fixup_f32 v32, v32, v27, 1.0
	v_pk_mul_f32 v[12:13], v[12:13], v[32:33] op_sel_hi:[1,0]
	v_pk_mul_f32 v[14:15], v[14:15], v[32:33] op_sel_hi:[1,0]
	v_pk_fma_f32 v[4:5], v[4:5], v[12:13], v[8:9]
	v_pk_fma_f32 v[6:7], v[6:7], v[14:15], v[10:11]
	v_bfe_u32 v8, v4, 16, 1
	v_add3_u32 v4, v4, v8, s9
	v_bfe_u32 v8, v5, 16, 1
	v_lshrrev_b32_e32 v4, 16, v4
	v_add3_u32 v5, v5, v8, s9
	v_and_or_b32 v4, v5, s20, v4
	v_bfe_u32 v5, v6, 16, 1
	v_add3_u32 v5, v6, v5, s9
	v_bfe_u32 v6, v7, 16, 1
	v_lshrrev_b32_e32 v5, 16, v5
	v_add3_u32 v6, v7, v6, s9
	v_and_or_b32 v5, v6, s20, v5
	global_store_dwordx2 v[28:29], v[4:5], off
	s_nop 0
	v_mov_b64_e32 v[4:5], v[136:137]
	v_mov_b64_e32 v[6:7], v[138:139]
	v_mov_b64_e32 v[8:9], v[140:141]
	v_mov_b64_e32 v[10:11], v[142:143]
	v_pk_mul_f32 v[12:13], v[36:37], v[32:33] op_sel_hi:[1,0]
	v_pk_mul_f32 v[14:15], v[34:35], v[32:33] op_sel_hi:[1,0]
	v_pk_mul_f32 v[2:3], v[2:3], v[32:33] op_sel_hi:[1,0]
	v_pk_mul_f32 v[0:1], v[0:1], v[32:33] op_sel_hi:[1,0]
	v_cmp_le_i32_e32 vcc, s66, v16
	s_or_b64 s[18:19], vcc, s[18:19]
	v_pk_add_f32 v[6:7], v[6:7], 1.0 op_sel_hi:[1,0]
	v_pk_add_f32 v[4:5], v[4:5], 1.0 op_sel_hi:[1,0]
	v_pk_fma_f32 v[6:7], v[6:7], v[14:15], v[10:11]
; __device__ __forceinline__ unsigned pk2(float lo, float hi) { return f2bf(lo) | (f2bf(hi) << 16); }
; __device__ __forceinline__ void ln_pass(const float* src, float* dstx, const float* lg, const float* lb, const float* msc, const float* msh, bf16_t* Hout, float* statout, const LnRows R) {
;     ...
;             for (int j = 0; j < 4; ++j) { const f32x4 c = *((const f32x4*)(msc + b * 6144) + lane + 64 * j), h = *((const f32x4*)(msh + b * 6144) + lane + 64 * j);
;                 const f32x4 w = v[j] * rstd * (c + 1.f) + h;
;                 u32x2 o; o.x = pk2(w.x, w.y); o.y = pk2(w.z, w.w);
;                 *((u32x2*)(Hout + (size_t)row * DM) + lane + 64 * j) = o; }
	v_pk_fma_f32 v[4:5], v[4:5], v[12:13], v[8:9]
	v_bfe_u32 v10, v6, 16, 1
	v_bfe_u32 v8, v4, 16, 1
	v_bfe_u32 v9, v5, 16, 1
	v_bfe_u32 v11, v7, 16, 1
	v_add3_u32 v4, v4, v8, s9
	v_add3_u32 v6, v6, v10, s9
	v_add3_u32 v5, v5, v9, s9
	v_add3_u32 v7, v7, v11, s9
	v_lshrrev_b32_e32 v4, 16, v4
	v_lshrrev_b32_e32 v6, 16, v6
	v_and_or_b32 v4, v5, s20, v4
	v_and_or_b32 v5, v7, s20, v6
	global_store_dwordx2 v[28:29], v[4:5], off offset:512
	s_nop 0
	v_mov_b64_e32 v[4:5], v[144:145]
	v_mov_b64_e32 v[6:7], v[146:147]
	v_mov_b64_e32 v[8:9], v[148:149]
	v_mov_b64_e32 v[10:11], v[150:151]
	v_pk_mul_f32 v[12:13], v[40:41], v[32:33] op_sel_hi:[1,0]
	v_pk_mul_f32 v[14:15], v[38:39], v[32:33] op_sel_hi:[1,0]
	v_pk_add_f32 v[6:7], v[6:7], 1.0 op_sel_hi:[1,0]
	v_pk_add_f32 v[4:5], v[4:5], 1.0 op_sel_hi:[1,0]
	v_pk_fma_f32 v[6:7], v[6:7], v[14:15], v[10:11]
	v_pk_fma_f32 v[4:5], v[4:5], v[12:13], v[8:9]
	v_bfe_u32 v10, v6, 16, 1
	v_bfe_u32 v8, v4, 16, 1
	v_bfe_u32 v9, v5, 16, 1
	v_bfe_u32 v11, v7, 16, 1
	v_add3_u32 v4, v4, v8, s9
	v_add3_u32 v6, v6, v10, s9
	v_add3_u32 v5, v5, v9, s9
	v_add3_u32 v7, v7, v11, s9
	v_lshrrev_b32_e32 v4, 16, v4
	v_lshrrev_b32_e32 v6, 16, v6
	v_and_or_b32 v4, v5, s20, v4
	v_and_or_b32 v5, v7, s20, v6
	global_store_dwordx2 v[28:29], v[4:5], off offset:1024
	s_nop 0
	v_mov_b64_e32 v[4:5], v[152:153]
	v_mov_b64_e32 v[6:7], v[154:155]
	v_mov_b64_e32 v[8:9], v[156:157]
	v_mov_b64_e32 v[10:11], v[158:159]
	v_pk_add_f32 v[6:7], v[6:7], 1.0 op_sel_hi:[1,0]
	v_pk_add_f32 v[4:5], v[4:5], 1.0 op_sel_hi:[1,0]
	v_pk_fma_f32 v[0:1], v[0:1], v[6:7], v[10:11]
	v_pk_fma_f32 v[2:3], v[2:3], v[4:5], v[8:9]
	v_bfe_u32 v6, v0, 16, 1
	v_bfe_u32 v4, v2, 16, 1
	v_bfe_u32 v5, v3, 16, 1
	v_bfe_u32 v7, v1, 16, 1
	v_add3_u32 v2, v2, v4, s9
	v_add3_u32 v0, v0, v6, s9
	v_add3_u32 v3, v3, v5, s9
	v_add3_u32 v1, v1, v7, s9
	v_lshrrev_b32_e32 v2, 16, v2
	v_lshrrev_b32_e32 v4, 16, v0
	v_and_or_b32 v0, v3, s20, v2
	v_and_or_b32 v1, v1, s20, v4
	global_store_dwordx2 v[28:29], v[0:1], off offset:1536
	v_lshl_add_u64 v[28:29], v[28:29], 0, s[14:15]
	s_andn2_b64 exec, exec, s[18:19]
	s_cbranch_execz .LBB0_2632
; __device__ __forceinline__ void ln_pass(const float* src, float* dstx, const float* lg, const float* lb, const float* msc, const float* msh, bf16_t* Hout, float* statout, const LnRows R) {
;     ...
;     for (int row = R.rbase + R.gw; row < R.rend; row += R.ngw) {
;         const f32x4* xr = (const f32x4*)(src + (size_t)row * DM) + lane;
;         f32x4 v[4];
; #pragma unroll
;         for (int j = 0; j < 4; ++j) v[j] = xr[64 * j];
;         if (lg) {
;             float s = 0.f;
; #pragma unroll
;             for (int j = 0; j < 4; ++j) s += (v[j].x + v[j].y) + (v[j].z + v[j].w);
;             const float mean = wave_sum(s) * (1.f / DM); float s2 = 0.f;
; #pragma unroll
;             for (int j = 0; j < 4; ++j) { v[j] = v[j] - mean; s2 += (v[j].x * v[j].x + v[j].y * v[j].y) + (v[j].z * v[j].z + v[j].w * v[j].w); }
;             const float rstd = 1.f / sqrtf(wave_sum(s2) * (1.f / DM) + 1e-5f);
;             if (statout && lane == 0) { statout[2 * row] = mean; statout[2 * row + 1] = rstd; }
;     ...
;             for (int j = 0; j < 4; ++j) { const f32x4 c = *((const f32x4*)(msc + b * 6144) + lane + 64 * j), h = *((const f32x4*)(msh + b * 6144) + lane + 64 * j);
.LBB0_2630:
	global_load_dwordx4 v[12:15], v[30:31], off offset:-3072
	global_load_dwordx4 v[8:11], v[30:31], off offset:-2048
	global_load_dwordx4 v[4:7], v[30:31], off offset:-1024
	global_load_dwordx4 v[0:3], v[30:31], off
	v_ashrrev_i32_e32 v160, 31, v16
	v_lshrrev_b32_e32 v160, 19, v160
	v_add_u32_e32 v160, v16, v160
	v_ashrrev_i32_e32 v160, 13, v160
	v_mul_i32_i24_e32 v160, 0x1800, v160
	v_ashrrev_i32_e32 v161, 31, v160
	v_lshlrev_b64 v[160:161], 2, v[160:161]
	v_lshl_add_u64 v[162:163], v[22:23], 0, v[160:161]
	v_lshl_add_u64 v[164:165], v[24:25], 0, v[160:161]
	global_load_dwordx4 v[128:131], v[162:163], off
	global_load_dwordx4 v[132:135], v[164:165], off
	global_load_dwordx4 v[136:139], v[162:163], off offset:1024
	global_load_dwordx4 v[140:143], v[164:165], off offset:1024
	global_load_dwordx4 v[144:147], v[162:163], off offset:2048
	global_load_dwordx4 v[148:151], v[164:165], off offset:2048
	global_load_dwordx4 v[152:155], v[162:163], off offset:3072
	global_load_dwordx4 v[156:159], v[164:165], off offset:3072
	s_waitcnt vmcnt(8)
	v_mov_b32_e32 v34, v13
	v_mov_b32_e32 v35, v14
	v_mov_b32_e32 v36, v12
	v_mov_b32_e32 v37, v15
	v_mov_b32_e32 v38, v9
	v_mov_b32_e32 v39, v10
	v_mov_b32_e32 v40, v8
	v_mov_b32_e32 v41, v11
	v_pk_add_f32 v[34:35], v[34:35], v[36:37]
	v_pk_add_f32 v[36:37], v[38:39], v[40:41]
	v_add_f32_e32 v27, v34, v35
	v_pk_add_f32 v[34:35], v[36:37], v[36:37] op_sel:[0,1] op_sel_hi:[1,0]
	v_add_f32_e32 v42, v4, v5
	v_add_f32_e32 v44, v6, v7
	v_mov_b32_e32 v47, v0
	v_mov_b32_e32 v43, v2
	v_mov_b32_e32 v45, v3
	v_add_f32_e32 v46, 0, v27
	v_mov_b32_e32 v35, v1
	v_pk_add_f32 v[38:39], v[42:43], v[44:45]
	v_pk_add_f32 v[34:35], v[46:47], v[34:35]
	s_nop 0
	v_pk_add_f32 v[34:35], v[34:35], v[38:39]
	s_nop 0
	v_add_f32_e32 v27, v34, v35
	v_mov_b32_e32 v32, v27
	s_nop 1
	v_mov_b32_dpp v32, v32 quad_perm:[1,0,3,2] row_mask:0xf bank_mask:0xf
	v_add_f32_e32 v27, v27, v32
	v_mov_b32_e32 v32, v27
	s_nop 1
	v_mov_b32_dpp v32, v32 quad_perm:[2,3,0,1] row_mask:0xf bank_mask:0xf
	v_add_f32_e32 v27, v27, v32
	v_mov_b32_e32 v32, v27
	s_nop 1
	v_mov_b32_dpp v32, v32 row_half_mirror row_mask:0xf bank_mask:0xf
	v_add_f32_e32 v27, v27, v32
	v_mov_b32_e32 v32, v27
	s_nop 1
	v_mov_b32_dpp v32, v32 row_mirror row_mask:0xf bank_mask:0xf
	v_add_f32_e32 v27, v27, v32
	s_nop 0
	v_readlane_b32 s21, v27, 16
	v_readlane_b32 s22, v27, 48
	v_readlane_b32 s0, v27, 0
	v_readlane_b32 s1, v27, 32
	v_mov_b32_e32 v34, s21
	v_mov_b32_e32 v35, s22
	v_pk_add_f32 v[34:35], s[0:1], v[34:35]
	s_nop 0
	v_add_f32_e32 v27, v34, v35
	v_fmamk_f32 v15, v27, 0xba800000, v15
	v_fmamk_f32 v13, v27, 0xba800000, v13
	v_fmamk_f32 v11, v27, 0xba800000, v11
	v_fmamk_f32 v9, v27, 0xba800000, v9
	v_fmamk_f32 v14, v27, 0xba800000, v14
	v_fmac_f32_e32 v12, 0xba800000, v27
	v_fmamk_f32 v10, v27, 0xba800000, v10
	v_fmac_f32_e32 v8, 0xba800000, v27
	v_fmamk_f32 v7, v27, 0xba800000, v7
	v_fmamk_f32 v5, v27, 0xba800000, v5
	v_mul_f32_e32 v32, v13, v13
	v_mul_f32_e32 v34, v15, v15
	v_mul_f32_e32 v35, v9, v9
	v_mul_f32_e32 v36, v11, v11
	v_fmamk_f32 v6, v27, 0xba800000, v6
	v_fmac_f32_e32 v4, 0xba800000, v27
	v_fmamk_f32 v3, v27, 0xba800000, v3
	v_fmamk_f32 v1, v27, 0xba800000, v1
	v_mul_f32_e32 v37, v5, v5
	v_mul_f32_e32 v38, v7, v7
	v_fmac_f32_e32 v32, v12, v12
	v_fmac_f32_e32 v34, v14, v14
	v_fmac_f32_e32 v35, v8, v8
	v_fmac_f32_e32 v36, v10, v10
	v_fmamk_f32 v2, v27, 0xba800000, v2
	v_fmac_f32_e32 v0, 0xba800000, v27
	v_mul_f32_e32 v39, v1, v1
	v_mul_f32_e32 v40, v3, v3
	v_fmac_f32_e32 v37, v4, v4
	v_fmac_f32_e32 v38, v6, v6
	v_add_f32_e32 v32, v32, v34
	v_add_f32_e32 v34, v35, v36
	v_fmac_f32_e32 v39, v0, v0
	v_fmac_f32_e32 v40, v2, v2
	v_add_f32_e32 v35, v37, v38
	v_add_f32_e32 v32, v32, v34
	v_add_f32_e32 v36, v39, v40
	v_add_f32_e32 v32, v35, v32
	v_add_f32_e32 v32, v36, v32
	v_mov_b32_e32 v34, v32
	s_nop 1
	v_mov_b32_dpp v34, v34 quad_perm:[1,0,3,2] row_mask:0xf bank_mask:0xf
	v_add_f32_e32 v32, v32, v34
	v_mov_b32_e32 v34, v32
	s_nop 1
	v_mov_b32_dpp v34, v34 quad_perm:[2,3,0,1] row_mask:0xf bank_mask:0xf
	v_add_f32_e32 v32, v32, v34
	v_mov_b32_e32 v34, v32
	s_nop 1
	v_mov_b32_dpp v34, v34 row_half_mirror row_mask:0xf bank_mask:0xf
	v_add_f32_e32 v32, v32, v34
	v_mov_b32_e32 v34, v32
	s_nop 1
	v_mov_b32_dpp v34, v34 row_mirror row_mask:0xf bank_mask:0xf
	v_add_f32_e32 v32, v32, v34
	s_nop 0
	v_readlane_b32 s1, v32, 16
	v_readlane_b32 s22, v32, 48
	v_readlane_b32 s0, v32, 0
	v_readlane_b32 s21, v32, 32
	v_mov_b32_e32 v32, s1
	v_mov_b32_e32 v34, s22
	v_add_f32_e32 v32, s0, v32
	v_add_f32_e32 v34, s21, v34
	v_add_f32_e32 v32, v32, v34
	v_fmamk_f32 v32, v32, 0x3a800000, v17
	v_mul_f32_e32 v34, 0x4f800000, v32
	v_cmp_gt_f32_e32 vcc, s7, v32
	s_nop 1
	v_cndmask_b32_e32 v32, v32, v34, vcc
	v_sqrt_f32_e32 v34, v32
	s_nop 0
	v_add_u32_e32 v35, -1, v34
	v_add_u32_e32 v36, 1, v34
	v_fma_f32 v37, -v35, v34, v32
	v_fma_f32 v38, -v36, v34, v32
	v_cmp_ge_f32_e64 s[0:1], 0, v37
	s_nop 1
	v_cndmask_b32_e64 v34, v34, v35, s[0:1]
	v_cmp_lt_f32_e64 s[0:1], 0, v38
	s_nop 1
	v_cndmask_b32_e64 v34, v34, v36, s[0:1]
	v_mul_f32_e32 v35, 0x37800000, v34
	v_cndmask_b32_e32 v34, v34, v35, vcc
	v_cmp_class_f32_e32 vcc, v32, v33
	s_nop 1
	v_cndmask_b32_e32 v32, v34, v32, vcc
	v_div_scale_f32 v34, s[0:1], v32, v32, 1.0
	v_rcp_f32_e32 v35, v34
	v_div_scale_f32 v36, vcc, 1.0, v32, 1.0
	v_fma_f32 v37, -v34, v35, 1.0
	v_fmac_f32_e32 v35, v37, v35
	v_mul_f32_e32 v37, v36, v35
	v_fma_f32 v38, -v34, v37, v36
	v_fmac_f32_e32 v37, v38, v35
	v_fma_f32 v34, -v34, v37, v36
	v_div_fmas_f32 v34, v34, v35, v37
	v_div_fixup_f32 v32, v34, v32, 1.0
	s_and_saveexec_b64 s[0:1], s[2:3]
	s_cbranch_execz .LBB0_2629
	v_mul_f32_e32 v34, 0x3a800000, v27
	v_ashrrev_i32_e32 v27, 31, v26
	v_lshl_add_u64 v[36:37], v[26:27], 2, s[12:13]
	v_mov_b32_e32 v35, v32
	global_store_dwordx2 v[36:37], v[34:35], off
	s_branch .LBB0_2629
